# pass2: ssq DPP chains interleaved; rstd computed once per 16-lane row and broadcast with DPP row_newbcast (fewer VALU/LDS ops)
# speedup vs baseline: 1.0072x; 1.0072x over previous
.LBB0_1330:
	s_add_i32 s26, s26, 1
	s_mov_b64 s[20:21], 0x10000
	v_and_b32_e32 v160, 3, v95
	v_bfe_u32 v161, v95, 2, 1
	v_lshlrev_b32_e32 v160, 5, v160
	v_lshl_add_u32 v160, v161, 9, v160
	v_add3_u32 v160, s27, v112, v160
	ds_read_b128 v[148:151], v160 offset:57344
	ds_read_b128 v[152:155], v160 offset:57360
	v_add_u32_e32 v125, s27, v122
	v_add_u32_e32 v125, v125, v99
	ds_read_u16 v162, v125 offset:48128
	ds_read_u16 v163, v125 offset:48400
	ds_read_u16 v164, v125 offset:48672
	ds_read_u16 v165, v125 offset:48944
	ds_read_u16 v166, v125 offset:52480
	ds_read_u16 v167, v125 offset:52752
	ds_read_u16 v168, v125 offset:53024
	ds_read_u16 v169, v125 offset:53296
	s_waitcnt vmcnt(4)
	s_waitcnt lgkmcnt(8)
	v_add_f32_e32 v156, v148, v149
	v_add_f32_e32 v157, v150, v151
	v_add_f32_e32 v158, v152, v153
	v_add_f32_e32 v156, v156, v157
	v_add_f32_e32 v159, v154, v155
	v_add_f32_e32 v158, v158, v159
	v_add_f32_e32 v156, v156, v158
	v_fmamk_f32 v156, v156, 0x3c000000, v218
	v_rsq_f32_e32 v156, v156
	s_nop 1
	v_mul_f32_dpp v170, v156, v62 row_newbcast:0 row_mask:0xf bank_mask:0xf
	s_waitcnt lgkmcnt(7)
	v_lshlrev_b32_e32 v171, 16, v162
	v_mul_f32_e32 v170, v87, v170
	v_mul_f32_e32 v170, v170, v171
	v_cvt_pk_bf16_f32 v172, v170, v170
	v_mul_f32_dpp v170, v156, v63 row_newbcast:1 row_mask:0xf bank_mask:0xf
	s_waitcnt lgkmcnt(6)
	v_lshlrev_b32_e32 v171, 16, v163
	v_mul_f32_e32 v170, v87, v170
	v_mul_f32_e32 v170, v170, v171
	v_cvt_pk_bf16_f32 v173, v170, v170
	v_mul_f32_dpp v170, v156, v64 row_newbcast:2 row_mask:0xf bank_mask:0xf
	s_waitcnt lgkmcnt(5)
	v_lshlrev_b32_e32 v171, 16, v164
	v_mul_f32_e32 v170, v87, v170
	v_mul_f32_e32 v170, v170, v171
	v_cvt_pk_bf16_f32 v174, v170, v170
	v_mul_f32_dpp v170, v156, v65 row_newbcast:3 row_mask:0xf bank_mask:0xf
	s_waitcnt lgkmcnt(4)
	v_lshlrev_b32_e32 v171, 16, v165
	v_mul_f32_e32 v170, v87, v170
	v_mul_f32_e32 v170, v170, v171
	v_cvt_pk_bf16_f32 v175, v170, v170
	v_mul_f32_dpp v170, v156, v58 row_newbcast:4 row_mask:0xf bank_mask:0xf
	s_waitcnt lgkmcnt(3)
	v_lshlrev_b32_e32 v171, 16, v166
	v_mul_f32_e32 v170, v87, v170
	v_mul_f32_e32 v170, v170, v171
	v_cvt_pk_bf16_f32 v176, v170, v170
	v_mul_f32_dpp v170, v156, v59 row_newbcast:5 row_mask:0xf bank_mask:0xf
	s_waitcnt lgkmcnt(2)
	v_lshlrev_b32_e32 v171, 16, v167
	v_mul_f32_e32 v170, v87, v170
	v_mul_f32_e32 v170, v170, v171
	v_cvt_pk_bf16_f32 v177, v170, v170
	v_mul_f32_dpp v170, v156, v60 row_newbcast:6 row_mask:0xf bank_mask:0xf
	s_waitcnt lgkmcnt(1)
	v_lshlrev_b32_e32 v171, 16, v168
	v_mul_f32_e32 v170, v87, v170
	v_mul_f32_e32 v170, v170, v171
	v_cvt_pk_bf16_f32 v178, v170, v170
	v_mul_f32_dpp v170, v156, v61 row_newbcast:7 row_mask:0xf bank_mask:0xf
	s_waitcnt lgkmcnt(0)
	v_lshlrev_b32_e32 v171, 16, v169
	v_mul_f32_e32 v170, v87, v170
	v_mul_f32_e32 v170, v170, v171
	v_cvt_pk_bf16_f32 v179, v170, v170
	ds_write_b16 v125, v172 offset:8704
	ds_write_b16 v125, v173 offset:8976
	ds_write_b16 v125, v174 offset:9248
	ds_write_b16 v125, v175 offset:9520
	ds_write_b16 v125, v176 offset:13056
	ds_write_b16 v125, v177 offset:13328
	ds_write_b16 v125, v178 offset:13600
	ds_write_b16 v125, v179 offset:13872
	s_cmp_lg_u32 s26, 8
	s_waitcnt lgkmcnt(0)
	s_barrier
	v_add3_u32 v58, s27, v93, v80
	ds_read_b128 v[58:61], v58 offset:8704
	s_waitcnt lgkmcnt(0)
	global_store_dwordx4 v[88:89], v[58:61], off
	v_lshl_add_u64 v[88:89], v[88:89], 0, s[20:21]
	s_mov_b64 s[20:21], 0x2c000
	v_lshl_add_u64 v[90:91], v[90:91], 0, s[20:21]
	s_cbranch_scc0 .LBB0_1325

.LBB0_1334:
	s_mul_i32 s22, s22, 0xe400
	s_add_i32 s27, s22, 0
	v_add3_u32 v125, s27, v104, v109
	v_add_u32_e32 v126, 0x1000, v125
	v_cvt_pk_bf16_f32 v58, v26, v27
	v_cvt_pk_bf16_f32 v59, v28, v29
	v_cvt_pk_bf16_f32 v60, v30, v31
	v_cvt_pk_bf16_f32 v61, v32, v33
	ds_read2_b64 v[62:65], v125 offset1:4
	ds_read2_b64 v[66:69], v126 offset0:32 offset1:36
	s_add_i32 s29, s27, s19
	s_waitcnt lgkmcnt(1)
	v_mfma_f32_16x16x32_bf16 v[62:65], v[62:65], v[58:61], 0
	s_waitcnt lgkmcnt(0)
	v_mfma_f32_16x16x32_bf16 v[58:61], v[66:69], v[58:61], 0
	v_cvt_pk_bf16_f32 v66, v34, v35
	v_cvt_pk_bf16_f32 v67, v36, v37
	v_cvt_pk_bf16_f32 v68, v38, v39
	v_cvt_pk_bf16_f32 v69, v40, v41
	ds_read2_b64 v[70:73], v125 offset0:8 offset1:12
	s_waitcnt lgkmcnt(0)
	v_mfma_f32_16x16x32_bf16 v[62:65], v[70:73], v[66:69], v[62:65]
	ds_read2_b64 v[70:73], v126 offset0:40 offset1:44
	s_waitcnt lgkmcnt(0)
	v_mfma_f32_16x16x32_bf16 v[58:61], v[70:73], v[66:69], v[58:61]
	v_cvt_pk_bf16_f32 v66, v42, v43
	v_cvt_pk_bf16_f32 v67, v44, v45
	v_cvt_pk_bf16_f32 v68, v46, v47
	v_cvt_pk_bf16_f32 v69, v48, v49
	ds_read2_b64 v[70:73], v125 offset0:16 offset1:20
	s_waitcnt lgkmcnt(0)
	v_mfma_f32_16x16x32_bf16 v[62:65], v[70:73], v[66:69], v[62:65]
	ds_read2_b64 v[70:73], v126 offset0:48 offset1:52
	s_waitcnt lgkmcnt(0)
	v_mfma_f32_16x16x32_bf16 v[58:61], v[70:73], v[66:69], v[58:61]
	v_cvt_pk_bf16_f32 v66, v50, v51
	v_cvt_pk_bf16_f32 v67, v52, v53
	v_cvt_pk_bf16_f32 v68, v54, v55
	v_cvt_pk_bf16_f32 v69, v56, v57
	ds_read2_b64 v[70:73], v125 offset0:24 offset1:28
	s_waitcnt lgkmcnt(0)
	v_mfma_f32_16x16x32_bf16 v[62:65], v[70:73], v[66:69], v[62:65]
	ds_read2_b64 v[70:73], v126 offset0:56 offset1:60
	v_add_u32_e32 v125, s27, v105
	v_add_u32_e32 v146, v125, v109
	s_waitcnt lgkmcnt(0)
	v_mfma_f32_16x16x32_bf16 v[58:61], v[70:73], v[66:69], v[58:61]
	ds_read_b128 v[66:69], v146 offset:8704
	ds_read_b128 v[70:73], v146
	ds_read_b128 v[126:129], v146 offset:13056
	ds_read_b128 v[130:133], v146 offset:4352
	s_waitcnt lgkmcnt(2)
	v_mfma_f32_16x16x32_bf16 v[70:73], v[66:69], v[70:73], 0
	s_waitcnt lgkmcnt(0)
	v_mfma_f32_16x16x32_bf16 v[66:69], v[66:69], v[130:133], 0
	v_mfma_f32_16x16x32_bf16 v[126:129], v[126:129], v[130:133], 0
	ds_read_b128 v[130:133], v146 offset:8768
	ds_read_b128 v[134:137], v146 offset:64
	ds_read_b128 v[138:141], v146 offset:13120
	ds_read_b128 v[142:145], v146 offset:4416
	s_waitcnt lgkmcnt(2)
	v_mfma_f32_16x16x32_bf16 v[70:73], v[130:133], v[134:137], v[70:73]
	s_waitcnt lgkmcnt(0)
	v_mfma_f32_16x16x32_bf16 v[66:69], v[130:133], v[142:145], v[66:69]
	v_mfma_f32_16x16x32_bf16 v[126:129], v[138:141], v[142:145], v[126:129]
	ds_read_b128 v[130:133], v146 offset:8832
	ds_read_b128 v[134:137], v146 offset:128
	ds_read_b128 v[138:141], v146 offset:13184
	ds_read_b128 v[142:145], v146 offset:4480
	s_waitcnt lgkmcnt(2)
	v_mfma_f32_16x16x32_bf16 v[70:73], v[130:133], v[134:137], v[70:73]
	s_waitcnt lgkmcnt(0)
	v_mfma_f32_16x16x32_bf16 v[66:69], v[130:133], v[142:145], v[66:69]
	v_mfma_f32_16x16x32_bf16 v[126:129], v[138:141], v[142:145], v[126:129]
	ds_read_b128 v[130:133], v146 offset:8896
	ds_read_b128 v[134:137], v146 offset:192
	ds_read_b128 v[138:141], v146 offset:13248
	ds_read_b128 v[142:145], v146 offset:4544
	s_waitcnt lgkmcnt(2)
	v_mfma_f32_16x16x32_bf16 v[70:73], v[130:133], v[134:137], v[70:73]
	v_add_u32_e32 v135, s27, v106
	s_waitcnt lgkmcnt(0)
	v_mfma_f32_16x16x32_bf16 v[130:133], v[130:133], v[142:145], v[66:69]
	v_mfma_f32_16x16x32_bf16 v[66:69], v[138:141], v[142:145], v[126:129]
	s_nop 3
	v_cndmask_b32_e64 v71, 0, v71, s[6:7]
	v_cndmask_b32_e64 v72, v72, 0, s[8:9]
	v_cndmask_b32_e64 v73, v73, 0, s[10:11]
	v_mov_b32_e32 v126, s55
	v_cndmask_b32_e64 v126, v70, v126, s[4:5]
	v_cndmask_b32_e64 v126, v126, v70, s[6:7]
	v_mov_b32_e32 v70, s55
	v_cndmask_b32_e64 v129, v68, 0, s[14:15]
	v_add_u32_e32 v68, v135, v123
	v_cndmask_b32_e64 v127, v66, v70, s[4:5]
	v_cndmask_b32_e64 v128, v67, 0, s[12:13]
	v_cndmask_b32_e64 v134, v69, 0, s[16:17]
	ds_read_b64_tr_b16 v[66:67], v68 offset:37888
	ds_read_b64_tr_b16 v[68:69], v68 offset:43008
	v_cvt_pk_bf16_f32 v70, v126, v71
	v_cvt_pk_bf16_f32 v71, v72, v73
	v_cvt_pk_bf16_f32 v72, v16, v16
	v_cvt_pk_bf16_f32 v73, v16, v16
	s_waitcnt lgkmcnt(0)
	v_mfma_f32_16x16x32_bf16 v[62:65], v[70:73], v[66:69], v[62:65]
	v_cvt_pk_bf16_f32 v70, v130, v131
	v_cvt_pk_bf16_f32 v71, v132, v133
	v_cvt_pk_bf16_f32 v72, v127, v128
	v_cvt_pk_bf16_f32 v73, v129, v134
	v_add_u32_e32 v134, v135, v110
	v_mfma_f32_16x16x32_bf16 v[58:61], v[70:73], v[66:69], v[58:61]
	ds_read_b128 v[70:73], v125 offset:56832
	ds_read_b64_tr_b16 v[128:129], v134 offset:32768
	ds_read_b64_tr_b16 v[126:127], v134 offset:27648
	ds_read_b64_tr_b16 v[130:131], v134 offset:27680
	s_waitcnt lgkmcnt(3)
	v_pk_mul_f32 v[26:27], v[26:27], v[70:71]
	v_add_u32_e32 v70, s27, v111
	v_pk_mul_f32 v[28:29], v[28:29], v[72:73]
	ds_read_b128 v[70:73], v70 offset:56832
	ds_read_b64_tr_b16 v[132:133], v134 offset:32800
	s_waitcnt lgkmcnt(3)
	v_mfma_f32_16x16x32_bf16 v[26:29], v[126:129], v[66:69], v[26:29]
	s_waitcnt lgkmcnt(1)
	v_pk_mul_f32 v[32:33], v[32:33], v[72:73]
	v_pk_mul_f32 v[30:31], v[30:31], v[70:71]
	ds_read_b128 v[70:73], v125 offset:56960
	ds_read_b64_tr_b16 v[126:127], v134 offset:27712
	ds_read_b64_tr_b16 v[128:129], v134 offset:32832
	s_waitcnt lgkmcnt(3)
	v_mfma_f32_16x16x32_bf16 v[30:33], v[130:133], v[66:69], v[30:33]
	s_waitcnt lgkmcnt(2)
	v_pk_mul_f32 v[36:37], v[36:37], v[72:73]
	v_pk_mul_f32 v[34:35], v[34:35], v[70:71]
	s_waitcnt lgkmcnt(0)
	s_nop 0
	v_mfma_f32_16x16x32_bf16 v[34:37], v[126:129], v[66:69], v[34:37]
	ds_read_b128 v[70:73], v125 offset:57024
	ds_read_b64_tr_b16 v[126:127], v134 offset:27744
	ds_read_b64_tr_b16 v[128:129], v134 offset:32864
	s_waitcnt lgkmcnt(2)
	v_pk_mul_f32 v[40:41], v[40:41], v[72:73]
	v_pk_mul_f32 v[38:39], v[38:39], v[70:71]
	s_waitcnt lgkmcnt(0)
	s_nop 0
	v_mfma_f32_16x16x32_bf16 v[38:41], v[126:129], v[66:69], v[38:41]
	ds_read_b128 v[70:73], v125 offset:57088
	ds_read_b64_tr_b16 v[126:127], v134 offset:27776
	ds_read_b64_tr_b16 v[128:129], v134 offset:32896
	s_waitcnt lgkmcnt(2)
	v_pk_mul_f32 v[44:45], v[44:45], v[72:73]
	v_pk_mul_f32 v[42:43], v[42:43], v[70:71]
	s_waitcnt lgkmcnt(0)
	s_nop 0
	v_mfma_f32_16x16x32_bf16 v[42:45], v[126:129], v[66:69], v[42:45]
	ds_read_b128 v[70:73], v125 offset:57152
	ds_read_b64_tr_b16 v[126:127], v134 offset:27808
	ds_read_b64_tr_b16 v[128:129], v134 offset:32928
	s_waitcnt lgkmcnt(2)
	v_pk_mul_f32 v[48:49], v[48:49], v[72:73]
	v_pk_mul_f32 v[46:47], v[46:47], v[70:71]
	s_waitcnt lgkmcnt(0)
	s_nop 0
	v_mfma_f32_16x16x32_bf16 v[46:49], v[126:129], v[66:69], v[46:49]
	ds_read_b128 v[70:73], v125 offset:57216
	ds_read_b64_tr_b16 v[126:127], v134 offset:27840
	ds_read_b64_tr_b16 v[128:129], v134 offset:32960
	s_waitcnt lgkmcnt(2)
	v_pk_mul_f32 v[52:53], v[52:53], v[72:73]
	v_pk_mul_f32 v[50:51], v[50:51], v[70:71]
	s_waitcnt lgkmcnt(0)
	s_nop 0
	v_mfma_f32_16x16x32_bf16 v[50:53], v[126:129], v[66:69], v[50:53]
	ds_read_b128 v[70:73], v125 offset:57280
	ds_read_b64_tr_b16 v[126:127], v134 offset:27872
	ds_read_b64_tr_b16 v[128:129], v134 offset:32992
	s_waitcnt lgkmcnt(2)
	v_pk_mul_f32 v[56:57], v[56:57], v[72:73]
	v_pk_mul_f32 v[54:55], v[54:55], v[70:71]
	s_waitcnt lgkmcnt(0)
	s_nop 0
	v_mfma_f32_16x16x32_bf16 v[54:57], v[126:129], v[66:69], v[54:57]
	v_mul_f32_e32 v148, v62, v62
	v_mul_f32_e32 v149, v63, v63
	v_mul_f32_e32 v150, v64, v64
	v_mul_f32_e32 v151, v65, v65
	v_mul_f32_e32 v152, v58, v58
	v_mul_f32_e32 v153, v59, v59
	v_mul_f32_e32 v154, v60, v60
	v_mul_f32_e32 v155, v61, v61
	v_add_u32_e32 v156, s29, v112
	v_add_f32_dpp v148, v148, v148 row_ror:8 row_mask:0xf bank_mask:0xf bound_ctrl:1
	v_add_f32_dpp v149, v149, v149 row_ror:8 row_mask:0xf bank_mask:0xf bound_ctrl:1
	v_add_f32_dpp v150, v150, v150 row_ror:8 row_mask:0xf bank_mask:0xf bound_ctrl:1
	v_add_f32_dpp v151, v151, v151 row_ror:8 row_mask:0xf bank_mask:0xf bound_ctrl:1
	v_add_f32_dpp v152, v152, v152 row_ror:8 row_mask:0xf bank_mask:0xf bound_ctrl:1
	v_add_f32_dpp v153, v153, v153 row_ror:8 row_mask:0xf bank_mask:0xf bound_ctrl:1
	v_add_f32_dpp v154, v154, v154 row_ror:8 row_mask:0xf bank_mask:0xf bound_ctrl:1
	v_add_f32_dpp v155, v155, v155 row_ror:8 row_mask:0xf bank_mask:0xf bound_ctrl:1
	v_add_f32_dpp v148, v148, v148 row_ror:4 row_mask:0xf bank_mask:0xf bound_ctrl:1
	v_add_f32_dpp v149, v149, v149 row_ror:4 row_mask:0xf bank_mask:0xf bound_ctrl:1
	v_add_f32_dpp v150, v150, v150 row_ror:4 row_mask:0xf bank_mask:0xf bound_ctrl:1
	v_add_f32_dpp v151, v151, v151 row_ror:4 row_mask:0xf bank_mask:0xf bound_ctrl:1
	v_add_f32_dpp v152, v152, v152 row_ror:4 row_mask:0xf bank_mask:0xf bound_ctrl:1
	v_add_f32_dpp v153, v153, v153 row_ror:4 row_mask:0xf bank_mask:0xf bound_ctrl:1
	v_add_f32_dpp v154, v154, v154 row_ror:4 row_mask:0xf bank_mask:0xf bound_ctrl:1
	v_add_f32_dpp v155, v155, v155 row_ror:4 row_mask:0xf bank_mask:0xf bound_ctrl:1
	v_add_f32_dpp v148, v148, v148 row_ror:2 row_mask:0xf bank_mask:0xf bound_ctrl:1
	v_add_f32_dpp v149, v149, v149 row_ror:2 row_mask:0xf bank_mask:0xf bound_ctrl:1
	v_add_f32_dpp v150, v150, v150 row_ror:2 row_mask:0xf bank_mask:0xf bound_ctrl:1
	v_add_f32_dpp v151, v151, v151 row_ror:2 row_mask:0xf bank_mask:0xf bound_ctrl:1
	v_add_f32_dpp v152, v152, v152 row_ror:2 row_mask:0xf bank_mask:0xf bound_ctrl:1
	v_add_f32_dpp v153, v153, v153 row_ror:2 row_mask:0xf bank_mask:0xf bound_ctrl:1
	v_add_f32_dpp v154, v154, v154 row_ror:2 row_mask:0xf bank_mask:0xf bound_ctrl:1
	v_add_f32_dpp v155, v155, v155 row_ror:2 row_mask:0xf bank_mask:0xf bound_ctrl:1
	v_add_f32_dpp v148, v148, v148 row_ror:1 row_mask:0xf bank_mask:0xf bound_ctrl:1
	v_add_f32_dpp v149, v149, v149 row_ror:1 row_mask:0xf bank_mask:0xf bound_ctrl:1
	v_add_f32_dpp v150, v150, v150 row_ror:1 row_mask:0xf bank_mask:0xf bound_ctrl:1
	v_add_f32_dpp v151, v151, v151 row_ror:1 row_mask:0xf bank_mask:0xf bound_ctrl:1
	v_add_f32_dpp v152, v152, v152 row_ror:1 row_mask:0xf bank_mask:0xf bound_ctrl:1
	v_add_f32_dpp v153, v153, v153 row_ror:1 row_mask:0xf bank_mask:0xf bound_ctrl:1
	v_add_f32_dpp v154, v154, v154 row_ror:1 row_mask:0xf bank_mask:0xf bound_ctrl:1
	v_add_f32_dpp v155, v155, v155 row_ror:1 row_mask:0xf bank_mask:0xf bound_ctrl:1
	s_and_saveexec_b64 s[22:23], s[2:3]
	ds_write_b32 v156, v148 offset:57344
	ds_write_b32 v156, v149 offset:57376
	ds_write_b32 v156, v150 offset:57408
	ds_write_b32 v156, v151 offset:57440
	ds_write_b32 v156, v152 offset:57856
	ds_write_b32 v156, v153 offset:57888
	ds_write_b32 v156, v154 offset:57920
	ds_write_b32 v156, v155 offset:57952
	s_or_b64 exec, exec, s[22:23]
	s_waitcnt lgkmcnt(0)
	s_barrier
	s_andn2_b64 vcc, exec, s[20:21]
	s_cbranch_vccnz .LBB0_1330
	v_add3_u32 v68, s28, v96, v120
	v_add_u32_e32 v126, s28, v122
	ds_read_b64_tr_b16 v[66:67], v68 offset:17408
	ds_read_b64_tr_b16 v[68:69], v68 offset:18688
	v_add_u32_e32 v127, v126, v98
	ds_read_u16 v128, v127 offset:17408
	s_waitcnt lgkmcnt(1)
	v_mfma_f32_16x16x32_bf16 v[70:73], v[4:7], v[66:69], 0
	s_waitcnt lgkmcnt(0)
	v_lshlrev_b32_e32 v129, 16, v128
	v_add_u32_e32 v128, v126, v99
	v_mfma_f32_16x16x32_bf16 v[66:69], v[0:3], v[66:69], 0
	ds_read_u16 v130, v128
	s_nop 2
	v_exp_f32_e32 v131, v70
	v_exp_f32_e32 v129, v129
	s_waitcnt lgkmcnt(0)
	v_lshlrev_b32_e32 v130, 16, v130
	v_mul_f32_e32 v130, v131, v130
	ds_bpermute_b32 v125, v121, v69
	v_cvt_pk_bf16_f32 v130, v130, v130
	ds_write_b16 v128, v130
	v_max_f32_e64 v130, -v70, -v70
	v_min_f32_e32 v130, 0x42e60000, v130
	s_waitcnt lgkmcnt(1)
	v_sub_f32_e32 v70, v125, v70
	v_exp_f32_e32 v130, v130
	v_exp_f32_e32 v70, v70
	v_sub_f32_e32 v129, 1.0, v129
	v_mul_f32_e32 v130, v130, v129
	v_mul_f32_e32 v70, v70, v129
	v_cvt_pk_bf16_f32 v130, v130, v130
	ds_write_b16 v128, v130 offset:8704
	v_cvt_pk_bf16_f32 v70, v70, v70
	ds_write_b16 v127, v70 offset:27648
	ds_read_u16 v70, v127 offset:17728
	ds_read_u16 v129, v128 offset:272
	v_exp_f32_e32 v130, v71
	s_waitcnt lgkmcnt(1)
	v_lshlrev_b32_e32 v70, 16, v70
	s_waitcnt lgkmcnt(0)
	v_lshlrev_b32_e32 v129, 16, v129
	v_mul_f32_e32 v129, v130, v129
	v_cvt_pk_bf16_f32 v129, v129, v129
	ds_write_b16 v128, v129 offset:272
	v_max_f32_e64 v129, -v71, -v71
	v_exp_f32_e32 v70, v70
	v_min_f32_e32 v129, 0x42e60000, v129
	v_sub_f32_e32 v71, v125, v71
	v_exp_f32_e32 v129, v129
	v_exp_f32_e32 v71, v71
	v_sub_f32_e32 v70, 1.0, v70
	v_exp_f32_e32 v130, v73
	v_mul_f32_e32 v129, v129, v70
	v_mul_f32_e32 v70, v71, v70
	v_cvt_pk_bf16_f32 v129, v129, v129
	ds_write_b16 v128, v129 offset:8976
	v_cvt_pk_bf16_f32 v70, v70, v70
	ds_write_b16 v127, v70 offset:27968
	ds_read_u16 v70, v127 offset:18048
	ds_read_u16 v71, v128 offset:544
	v_exp_f32_e32 v129, v72
	s_waitcnt lgkmcnt(1)
	v_lshlrev_b32_e32 v70, 16, v70
	s_waitcnt lgkmcnt(0)
	v_lshlrev_b32_e32 v71, 16, v71
	v_mul_f32_e32 v71, v129, v71
	v_cvt_pk_bf16_f32 v71, v71, v71
	ds_write_b16 v128, v71 offset:544
	v_max_f32_e64 v71, -v72, -v72
	v_exp_f32_e32 v70, v70
	v_min_f32_e32 v71, 0x42e60000, v71
	v_exp_f32_e32 v71, v71
	v_sub_f32_e32 v70, 1.0, v70
	v_mul_f32_e32 v71, v71, v70
	v_cvt_pk_bf16_f32 v71, v71, v71
	ds_write_b16 v128, v71 offset:9248
	v_sub_f32_e32 v71, v125, v72
	v_exp_f32_e32 v71, v71
	v_add_u32_e32 v72, v126, v101
	v_mul_f32_e32 v70, v71, v70
	v_cvt_pk_bf16_f32 v70, v70, v70
	ds_write_b16 v127, v70 offset:28288
	v_add_u32_e32 v70, v126, v100
	ds_read_u16 v71, v70 offset:17408
	ds_read_u16 v129, v72
	s_waitcnt lgkmcnt(1)
	v_lshlrev_b32_e32 v71, 16, v71
	s_waitcnt lgkmcnt(0)
	v_lshlrev_b32_e32 v129, 16, v129
	v_mul_f32_e32 v129, v130, v129
	v_cvt_pk_bf16_f32 v129, v129, v129
	ds_write_b16 v72, v129
	v_max_f32_e64 v129, -v73, -v73
	v_exp_f32_e32 v71, v71
	v_min_f32_e32 v129, 0x42e60000, v129
	v_exp_f32_e32 v129, v129
	v_sub_f32_e32 v71, 1.0, v71
	v_mul_f32_e32 v129, v129, v71
	v_cvt_pk_bf16_f32 v129, v129, v129
	ds_write_b16 v72, v129 offset:8704
	v_sub_f32_e32 v72, v125, v73
	v_exp_f32_e32 v72, v72
	s_nop 0
	v_mul_f32_e32 v71, v72, v71
	v_cvt_pk_bf16_f32 v71, v71, v71
	ds_write_b16 v70, v71 offset:27648
	ds_read_u16 v70, v127 offset:22528
	ds_read_u16 v71, v128 offset:4352
	v_exp_f32_e32 v72, v66
	s_waitcnt lgkmcnt(1)
	v_lshlrev_b32_e32 v70, 16, v70
	s_waitcnt lgkmcnt(0)
	v_lshlrev_b32_e32 v71, 16, v71
	v_mul_f32_e32 v71, v72, v71
	v_cvt_pk_bf16_f32 v71, v71, v71
	ds_write_b16 v128, v71 offset:4352
	v_max_f32_e64 v71, -v66, -v66
	v_exp_f32_e32 v70, v70
	v_min_f32_e32 v71, 0x42e60000, v71
	v_sub_f32_e32 v66, v125, v66
	v_exp_f32_e32 v71, v71
	v_exp_f32_e32 v66, v66
	v_sub_f32_e32 v70, 1.0, v70
	v_mul_f32_e32 v71, v71, v70
	v_mul_f32_e32 v66, v66, v70
	v_cvt_pk_bf16_f32 v71, v71, v71
	ds_write_b16 v128, v71 offset:13056
	v_cvt_pk_bf16_f32 v66, v66, v66
	ds_write_b16 v127, v66 offset:32768
	ds_read_u16 v66, v127 offset:22848
	ds_read_u16 v70, v128 offset:4624
	v_exp_f32_e32 v71, v67
	s_waitcnt lgkmcnt(1)
	v_lshlrev_b32_e32 v66, 16, v66
	s_waitcnt lgkmcnt(0)
	v_lshlrev_b32_e32 v70, 16, v70
	v_mul_f32_e32 v70, v71, v70
	v_cvt_pk_bf16_f32 v70, v70, v70
	ds_write_b16 v128, v70 offset:4624
	v_max_f32_e64 v70, -v67, -v67
	v_exp_f32_e32 v66, v66
	v_min_f32_e32 v70, 0x42e60000, v70
	v_sub_f32_e32 v67, v125, v67
	v_exp_f32_e32 v70, v70
	v_exp_f32_e32 v67, v67
	v_sub_f32_e32 v66, 1.0, v66
	v_exp_f32_e32 v71, v69
	v_mul_f32_e32 v70, v70, v66
	v_mul_f32_e32 v66, v67, v66
	v_cvt_pk_bf16_f32 v70, v70, v70
	ds_write_b16 v128, v70 offset:13328
	v_cvt_pk_bf16_f32 v66, v66, v66
	ds_write_b16 v127, v66 offset:33088
	ds_read_u16 v66, v127 offset:23168
	ds_read_u16 v67, v128 offset:4896
	v_exp_f32_e32 v70, v68
	s_waitcnt lgkmcnt(1)
	v_lshlrev_b32_e32 v66, 16, v66
	s_waitcnt lgkmcnt(0)
	v_lshlrev_b32_e32 v67, 16, v67
	v_mul_f32_e32 v67, v70, v67
	v_cvt_pk_bf16_f32 v67, v67, v67
	ds_write_b16 v128, v67 offset:4896
	v_max_f32_e64 v67, -v68, -v68
	v_exp_f32_e32 v66, v66
	v_min_f32_e32 v67, 0x42e60000, v67
	v_exp_f32_e32 v67, v67
	v_sub_f32_e32 v66, 1.0, v66
	v_mul_f32_e32 v67, v67, v66
	v_cvt_pk_bf16_f32 v67, v67, v67
	ds_write_b16 v128, v67 offset:13600
	v_sub_f32_e32 v67, v125, v68
	v_exp_f32_e32 v67, v67
	v_add_u32_e32 v68, v126, v103
	v_mul_f32_e32 v66, v67, v66
	v_cvt_pk_bf16_f32 v66, v66, v66
	ds_write_b16 v127, v66 offset:33408
	v_add_u32_e32 v66, v126, v102
	ds_read_u16 v67, v66 offset:17408
	ds_read_u16 v70, v68
	s_waitcnt lgkmcnt(1)
	v_lshlrev_b32_e32 v67, 16, v67
	s_waitcnt lgkmcnt(0)
	v_lshlrev_b32_e32 v70, 16, v70
	v_mul_f32_e32 v70, v71, v70
	v_cvt_pk_bf16_f32 v70, v70, v70
	ds_write_b16 v68, v70
	v_max_f32_e64 v70, -v69, -v69
	v_exp_f32_e32 v67, v67
	v_min_f32_e32 v70, 0x42e60000, v70
	v_exp_f32_e32 v70, v70
	v_sub_f32_e32 v67, 1.0, v67
	v_mul_f32_e32 v70, v70, v67
	v_cvt_pk_bf16_f32 v70, v70, v70
	ds_write_b16 v68, v70 offset:8704
	v_sub_f32_e32 v68, v125, v69
	v_exp_f32_e32 v68, v68
	s_nop 0
	v_mul_f32_e32 v67, v68, v67
	v_cvt_pk_bf16_f32 v67, v67, v67
	ds_write_b16 v66, v67 offset:27648
	s_and_saveexec_b64 s[20:21], s[0:1]
	s_cbranch_execz .LBB0_1329
	v_exp_f32_e32 v66, v125
	v_add_u32_e32 v67, s28, v124
	ds_write_b32 v67, v66 offset:56832
	s_branch .LBB0_1329
